# v3_sw_il
# speedup vs baseline: 1.2430x; 1.2430x over previous
.LBB0_429:
	s_cmp_eq_u32 s15, 0x60800
	s_mov_b32 s2, 0x10000
	s_cbranch_scc1 .LBB0_428
	s_and_b32 s2, s13, 0x10000
	s_xor_b32 s10, s2, 0x10000
	s_add_i32 s35, s22, s10
	s_add_i32 s36, s15, 0xfffa0000
	s_add_i32 s37, s35, 0x8000
	s_mov_b32 s10, s66
	s_mov_b32 s11, s67
	s_waitcnt lgkmcnt(0)
	v_add_u32_e32 v158, s2, v207
	v_add_u32_e32 v159, s2, v204
	v_xor_b32_e32 v208, 64, v158
	ds_read_b128 v[50:53], v159 offset:0
	ds_read_b128 v[54:57], v159 offset:0x800
	ds_read_b128 v[58:61], v159 offset:0x1000
	ds_read_b128 v[78:81], v159 offset:0x1800
	ds_read_b128 v[98:101], v158 offset:0
	ds_read_b128 v[118:121], v158 offset:0x800
	s_setprio 1
	ds_read_b128 v[138:141], v158 offset:0x1000
	s_mov_b32 m0, s35
	s_nop 0
	buffer_load_dwordx4 v201, s[64:67], s36 offen lds
	s_mov_b32 m0, s37
	s_nop 0
	buffer_load_dwordx4 v201, s[8:11], s36 offen lds
	s_waitcnt lgkmcnt(2)
	s_nop 0
	v_mfma_f32_16x16x32_bf16 v[150:153], v[98:101], v[50:53], v[150:153]
	v_mfma_f32_16x16x32_bf16 v[154:157], v[98:101], v[54:57], v[154:157]
	v_mfma_f32_16x16x32_bf16 v[142:145], v[98:101], v[58:61], v[142:145]
	v_mfma_f32_16x16x32_bf16 v[98:101], v[98:101], v[78:81], v[146:149]
	s_add_i32 m0, s35, 0x2000
	s_add_i32 s36, s15, 0xfffc0000
	buffer_load_dwordx4 v201, s[64:67], s36 offen lds
	ds_read_b128 v[146:149], v158 offset:0x1800
	s_waitcnt lgkmcnt(2)
	s_nop 0
	v_mfma_f32_16x16x32_bf16 v[130:133], v[118:121], v[50:53], v[130:133]
	v_mfma_f32_16x16x32_bf16 v[134:137], v[118:121], v[54:57], v[134:137]
	v_mfma_f32_16x16x32_bf16 v[122:125], v[118:121], v[58:61], v[122:125]
	v_mfma_f32_16x16x32_bf16 v[118:121], v[118:121], v[78:81], v[126:129]
	s_add_i32 m0, s35, 0xa000
	s_nop 0
	buffer_load_dwordx4 v201, s[8:11], s36 offen lds
	ds_read_b128 v[126:129], v158 offset:0x2000
	s_waitcnt lgkmcnt(2)
	s_nop 0
	v_mfma_f32_16x16x32_bf16 v[110:113], v[138:141], v[50:53], v[110:113]
	v_mfma_f32_16x16x32_bf16 v[114:117], v[138:141], v[54:57], v[114:117]
	v_mfma_f32_16x16x32_bf16 v[102:105], v[138:141], v[58:61], v[102:105]
	v_mfma_f32_16x16x32_bf16 v[106:109], v[138:141], v[78:81], v[106:109]
	s_add_i32 m0, s35, 0x4000
	s_add_i32 s36, s15, 0xfffe0000
	buffer_load_dwordx4 v201, s[64:67], s36 offen lds
	ds_read_b128 v[138:141], v158 offset:0x2800
	s_waitcnt lgkmcnt(2)
	s_nop 0
	v_mfma_f32_16x16x32_bf16 v[90:93], v[146:149], v[50:53], v[90:93]
	v_mfma_f32_16x16x32_bf16 v[94:97], v[146:149], v[54:57], v[94:97]
	v_mfma_f32_16x16x32_bf16 v[82:85], v[146:149], v[58:61], v[82:85]
	v_mfma_f32_16x16x32_bf16 v[86:89], v[146:149], v[78:81], v[86:89]
	s_add_i32 m0, s35, 0xc000
	s_nop 0
	buffer_load_dwordx4 v201, s[8:11], s36 offen lds
	ds_read_b128 v[146:149], v158 offset:0x3000
	s_waitcnt lgkmcnt(2)
	s_nop 0
	v_mfma_f32_16x16x32_bf16 v[70:73], v[126:129], v[50:53], v[70:73]
	v_mfma_f32_16x16x32_bf16 v[74:77], v[126:129], v[54:57], v[74:77]
	v_mfma_f32_16x16x32_bf16 v[62:65], v[126:129], v[58:61], v[62:65]
	v_mfma_f32_16x16x32_bf16 v[66:69], v[126:129], v[78:81], v[66:69]
	s_add_i32 m0, s35, 0x6000
	s_nop 0
	buffer_load_dwordx4 v201, s[64:67], s15 offen lds
	ds_read_b128 v[126:129], v158 offset:0x3800
	s_waitcnt lgkmcnt(2)
	v_xor_b32_e32 v166, 64, v159
	v_mfma_f32_16x16x32_bf16 v[42:45], v[138:141], v[50:53], v[42:45]
	v_mfma_f32_16x16x32_bf16 v[46:49], v[138:141], v[54:57], v[46:49]
	v_mfma_f32_16x16x32_bf16 v[34:37], v[138:141], v[58:61], v[34:37]
	v_mfma_f32_16x16x32_bf16 v[38:41], v[138:141], v[78:81], v[38:41]
	s_add_i32 m0, s35, 0xe000
	s_nop 0
	buffer_load_dwordx4 v201, s[8:11], s15 offen lds
	ds_read_b128 v[138:141], v166 offset:0
	ds_read_b128 v[158:161], v166 offset:0x800
	ds_read_b128 v[162:165], v166 offset:0x1000
	s_waitcnt lgkmcnt(4)
	s_nop 0
	v_mfma_f32_16x16x32_bf16 v[26:29], v[146:149], v[50:53], v[26:29]
	v_mfma_f32_16x16x32_bf16 v[30:33], v[146:149], v[54:57], v[30:33]
	v_mfma_f32_16x16x32_bf16 v[18:21], v[146:149], v[58:61], v[18:21]
	v_mfma_f32_16x16x32_bf16 v[22:25], v[146:149], v[78:81], v[22:25]
	ds_read_b128 v[166:169], v166 offset:0x1800
	ds_read_b128 v[146:149], v208 offset:0
	ds_read_b128 v[174:177], v208 offset:0x800
	s_waitcnt lgkmcnt(6)
	s_nop 0
	v_mfma_f32_16x16x32_bf16 v[10:13], v[126:129], v[50:53], v[10:13]
	v_mfma_f32_16x16x32_bf16 v[14:17], v[126:129], v[54:57], v[14:17]
	v_mfma_f32_16x16x32_bf16 v[2:5], v[126:129], v[58:61], v[2:5]
	v_mfma_f32_16x16x32_bf16 v[6:9], v[126:129], v[78:81], v[6:9]
	ds_read_b128 v[50:53], v208 offset:0x1000
	s_waitcnt lgkmcnt(2)
	s_nop 0
	v_mfma_f32_16x16x32_bf16 v[150:153], v[146:149], v[138:141], v[150:153]
	v_mfma_f32_16x16x32_bf16 v[154:157], v[146:149], v[158:161], v[154:157]
	v_mfma_f32_16x16x32_bf16 v[142:145], v[146:149], v[162:165], v[142:145]
	v_mfma_f32_16x16x32_bf16 v[146:149], v[146:149], v[166:169], v[98:101]
	ds_read_b128 v[54:57], v208 offset:0x1800
	s_waitcnt lgkmcnt(2)
	s_nop 0
	v_mfma_f32_16x16x32_bf16 v[130:133], v[174:177], v[138:141], v[130:133]
	v_mfma_f32_16x16x32_bf16 v[134:137], v[174:177], v[158:161], v[134:137]
	v_mfma_f32_16x16x32_bf16 v[122:125], v[174:177], v[162:165], v[122:125]
	v_mfma_f32_16x16x32_bf16 v[126:129], v[174:177], v[166:169], v[118:121]
	ds_read_b128 v[58:61], v208 offset:0x2000
	s_waitcnt lgkmcnt(2)
	s_nop 0
	v_mfma_f32_16x16x32_bf16 v[110:113], v[50:53], v[138:141], v[110:113]
	v_mfma_f32_16x16x32_bf16 v[114:117], v[50:53], v[158:161], v[114:117]
	v_mfma_f32_16x16x32_bf16 v[102:105], v[50:53], v[162:165], v[102:105]
	v_mfma_f32_16x16x32_bf16 v[106:109], v[50:53], v[166:169], v[106:109]
	ds_read_b128 v[50:53], v208 offset:0x2800
	s_waitcnt lgkmcnt(2)
	s_nop 0
	v_mfma_f32_16x16x32_bf16 v[90:93], v[54:57], v[138:141], v[90:93]
	v_mfma_f32_16x16x32_bf16 v[94:97], v[54:57], v[158:161], v[94:97]
	v_mfma_f32_16x16x32_bf16 v[82:85], v[54:57], v[162:165], v[82:85]
	v_mfma_f32_16x16x32_bf16 v[86:89], v[54:57], v[166:169], v[86:89]
	ds_read_b128 v[54:57], v208 offset:0x3000
	s_waitcnt lgkmcnt(2)
	s_nop 0
	v_mfma_f32_16x16x32_bf16 v[70:73], v[58:61], v[138:141], v[70:73]
	v_mfma_f32_16x16x32_bf16 v[74:77], v[58:61], v[158:161], v[74:77]
	v_mfma_f32_16x16x32_bf16 v[62:65], v[58:61], v[162:165], v[62:65]
	v_mfma_f32_16x16x32_bf16 v[66:69], v[58:61], v[166:169], v[66:69]
	ds_read_b128 v[58:61], v208 offset:0x3800
	s_waitcnt lgkmcnt(2)
	s_nop 0
	v_mfma_f32_16x16x32_bf16 v[42:45], v[50:53], v[138:141], v[42:45]
	v_mfma_f32_16x16x32_bf16 v[46:49], v[50:53], v[158:161], v[46:49]
	v_mfma_f32_16x16x32_bf16 v[34:37], v[50:53], v[162:165], v[34:37]
	v_mfma_f32_16x16x32_bf16 v[38:41], v[50:53], v[166:169], v[38:41]
	s_waitcnt lgkmcnt(1)
	s_nop 0
	v_mfma_f32_16x16x32_bf16 v[26:29], v[54:57], v[138:141], v[26:29]
	v_mfma_f32_16x16x32_bf16 v[30:33], v[54:57], v[158:161], v[30:33]
	v_mfma_f32_16x16x32_bf16 v[18:21], v[54:57], v[162:165], v[18:21]
	v_mfma_f32_16x16x32_bf16 v[22:25], v[54:57], v[166:169], v[22:25]
	s_waitcnt lgkmcnt(0)
	s_nop 0
	v_mfma_f32_16x16x32_bf16 v[10:13], v[58:61], v[138:141], v[10:13]
	v_mfma_f32_16x16x32_bf16 v[14:17], v[58:61], v[158:161], v[14:17]
	v_mfma_f32_16x16x32_bf16 v[2:5], v[58:61], v[162:165], v[2:5]
	v_mfma_f32_16x16x32_bf16 v[6:9], v[58:61], v[166:169], v[6:9]
	s_setprio 0
	s_waitcnt vmcnt(0)
	s_add_i32 s13, s13, 0x10000
	s_addk_i32 s15, 0x80
	s_cmp_eq_u32 s15, 0x60880
	s_barrier
	s_cbranch_scc1 .LBB0_431
	s_branch .LBB0_429
